# P7: stronger Horner-length rebalance: sample-unit waves take chunks {s0,31-s0}, others {32+t,63-t}
# speedup vs baseline: 1.0008x; 1.0008x over previous
; template <int PASS> __device__ __forceinline__ void ssm_unit(int unit, int lane, LAS unsigned char* wl, const bf16* X2, const float* slots, float* RSTD, const float* gmix, const float* AB, const float* A128, const bf16* BB, const bf16* CC, ...
;     ...
;     { const f32x2 abA = *(const f32x2*)(AB + (size_t)(g * 64 + n) * 2), abB = *(const f32x2*)(AB + (size_t)(g * 64 + n + 32) * 2);
;       aA = {abA.x, abA.y}; aB = {abB.x, abB.y};
;       cpx t = cmul(aA, aA); t = cmul(t, t); aA8 = cmul(t, t); t = cmul(aB, aB); t = cmul(t, t); aB8 = cmul(t, t); }
;     bf16x8 bbf[4];
; #pragma unroll
;     for (int b = 0; b < 4; ++b) bbf[b] = ld8_bf16(BB + ((size_t)g * 128 + b * 32 + n) * 16 + 8 * hi);
;     cpx SA = {0.f, 0.f}, SB = {0.f, 0.f};
;     if (PASS == 2) {
;         if (smp) { const size_t o = (size_t)(sc - 128) * 4096 + g * 64 + n; SA = {h0r[o], h0i[o]}; SB = {h0r[o + 32], h0i[o + 32]}; }
;         else {
;             const f32x2 pA = *(const f32x2*)(A128 + (size_t)(g * 64 + n) * 2), pB = *(const f32x2*)(A128 + (size_t)(g * 64 + n + 32) * 2);
;             const cpx qA = {pA.x, pA.y}, qB = {pB.x, pB.y};
;             const int c0 = sc & ~63, nc = sc & 63;
;             const float* ep = E + ((size_t)c0 * 4096 + g * 64 + n) * 2;
; #pragma unroll 4
;             for (int c = 0; c < nc; ++c) { const f32x2 eA = *(const f32x2*)(ep + (size_t)c * 8192), eB = *(const f32x2*)(ep + (size_t)c * 8192 + 64);
;                 SA = cfma(qA, SA, (cpx){eA.x, eA.y}); SB = cfma(qB, SB, (cpx){eB.x, eB.y}); }
;         }
;     }
;     LAS unsigned char* Sl = wl;
;     LAS float* Ul = (LAS float*)(wl + 128 * SSM_IROW);
;     bf16x8 ccf[4]; f32x4 dv = {0.f, 0.f, 0.f, 0.f};
;     const int c16 = lane & 15, kq = lane >> 4;
;     if (PASS == 2) {
; #pragma unroll
; __global__ void __launch_bounds__(512, 2) mk_fwd(Params p) {
;     ...
;         for (int u0 = gw; u0 < 144 * 64; u0 += NGW) {
;             int u = u0;
;             if (u0 < 128 * 64) { const int k = u0 >> 11, s0 = (u0 >> 6) & 31, j = (k & 1) ? 63 - s0 : s0; u = (((k >> 1) * 64 + j) << 6) | (u0 & 63); }
;             ssm_unit<2>(u, lane, wl, WSB(bf16, WS_RA), WSB(float, WS_SL2), WSB(float, WS_RSTD), p.in[6] + D, WSB(float, WS_AB), WSB(float, WS_A128), WSB(bf16, WS_BB), WSB(bf16, WS_CC), p.in[20], WSB(float, WS_E), p.in[4], p.in[5], WSB(bf16, WS_RD), OUTP(O_RP), OUTP(O_IP), OUTP(O_RS), OUTP(O_IS));
.LBB0_720:
	s_and_b32 s4, s74, 0x7c0
	s_and_b32 s5, s74, 0x800
	s_and_b32 s98, s4, 0x400
	s_lshl_b32 s99, s98, 1
	s_or_b32 s99, s99, s98
	s_add_i32 s98, s98, 0x7c0
	s_xor_b32 s14, s4, s98
	s_xor_b32 s4, s4, s99
	s_cmp_eq_u32 s5, 0
	s_cselect_b32 s4, s4, s14
	s_and_b32 s5, s74, 0xfffff03f
	s_or_b32 s4, s4, s5
	s_cmpk_lt_i32 s74, 0x2000
	s_cselect_b32 s72, s4, s74
	s_and_b32 s4, s72, 63
	s_ashr_i32 s75, s72, 6
	s_cmpk_gt_i32 s75, 0x7f
	s_cselect_b64 s[46:47], -1, 0
	s_cmpk_lt_i32 s75, 0x80
	s_cselect_b64 s[44:45], -1, 0
	s_lshl_b32 s34, s4, 6
	v_or_b32_e32 v1, s34, v162
	v_lshlrev_b32_e32 v0, 1, v1
	v_lshlrev_b32_e32 v2, 3, v1
	v_or_b32_e32 v1, 64, v0
	s_lshl_b32 s5, s4, 11
	v_lshlrev_b32_e32 v1, 2, v1
	global_load_dwordx2 v[128:129], v2, s[64:65]
	global_load_dwordx2 v[130:131], v1, s[64:65]
	v_or_b32_e32 v2, s5, v153
	v_lshlrev_b32_e32 v112, 1, v2
	v_lshl_add_u64 v[2:3], v[114:115], 0, v[112:113]
	global_load_dwordx4 v[64:67], v[2:3], off
	global_load_dwordx4 v[68:71], v[2:3], off offset:1024
	global_load_dwordx4 v[72:75], v[2:3], off offset:2048
	global_load_dwordx4 v[76:79], v[2:3], off offset:3072
	s_and_b32 s98, s72, 0xffffffc0
	s_addk_i32 s98, 0x2000
	s_lshl_b32 s99, s75, 7
	s_and_b64 s[100:101], s[46:47], exec
	s_cselect_b32 s98, s98, s99
	v_or_b32_e32 v207, s5, v159
	v_lshlrev_b32_e32 v208, 1, v207
	v_mov_b32_e32 v209, 0
	v_lshl_add_u64 v[210:211], v[116:117], 0, v[208:209]
	global_load_dwordx4 v[80:83], v[210:211], off
	global_load_dwordx4 v[84:87], v[210:211], off offset:64
	global_load_dwordx4 v[88:91], v[210:211], off offset:128
	global_load_dwordx4 v[92:95], v[210:211], off offset:192
	v_lshl_add_u64 v[210:211], v[118:119], 0, s[34:35]
	global_load_dwordx4 v[96:99], v[210:211], off
	v_lshl_add_u64 v[210:211], v[120:121], 0, s[34:35]
	global_load_dwordx4 v[100:103], v[210:211], off offset:16
	global_load_dwordx4 v[104:107], v[210:211], off
	v_or_b32_e32 v214, s98, v157
	v_ashrrev_i32_e32 v215, 31, v214
	v_lshlrev_b64 v[216:217], 11, v[214:215]
	v_lshl_add_u64 v[216:217], s[20:21], 0, v[216:217]
	s_lshl_b32 s100, s4, 5
	s_mov_b32 s101, s35
	v_lshl_add_u64 v[216:217], v[216:217], 0, s[100:101]
	v_mov_b32_e32 v218, v126
	v_mov_b32_e32 v219, 0
	v_lshl_add_u64 v[216:217], v[216:217], 0, v[218:219]
	v_lshl_add_u64 v[220:221], v[214:215], 2, s[22:23]
	global_load_dwordx4 v[202:205], v[216:217], off
	s_nop 0
	global_load_dword v206, v[220:221], off
	s_mov_b64 s[68:69], -1
	s_and_b64 vcc, exec, s[44:45]
	s_cbranch_vccz .LBB0_731
	s_bfe_u32 s70, s72, 0x60006
	s_cmp_eq_u32 s70, 0
	s_cbranch_scc1 .LBB0_726
	v_lshlrev_b32_e32 v0, 2, v0
	global_load_dwordx2 v[4:5], v1, s[66:67]
	global_load_dwordx2 v[8:9], v0, s[66:67]
	s_and_b32 s68, s75, 0xffffffc0
	s_ashr_i32 s69, s68, 31
	s_lshl_b64 s[68:69], s[68:69], 12
	s_cmp_lt_u32 s70, 4
	s_waitcnt vmcnt(1)
	v_xor_b32_e32 v0, 0x80000000, v5
	v_mov_b32_e32 v2, v4
	v_mov_b32_e32 v3, v4
	v_mov_b32_e32 v1, v5
	s_waitcnt vmcnt(0)
	v_xor_b32_e32 v4, 0x80000000, v9
	v_mov_b32_e32 v6, v8
	v_mov_b32_e32 v7, v8
	v_mov_b32_e32 v5, v9
	s_cbranch_scc1 .LBB0_727
	s_and_b32 s70, s75, 60
	s_add_u32 s76, s34, s68
	s_addc_u32 s77, 0, s69
	v_lshl_add_u64 v[8:9], s[76:77], 0, v[162:163]
	v_mov_b32_e32 v132, 0
	v_lshl_add_u64 v[8:9], v[8:9], 3, s[36:37]
	s_mov_b32 s71, 0
	v_mov_b32_e32 v133, v132
	v_mov_b32_e32 v164, v132
	v_mov_b32_e32 v165, v132
